# RNN conv stage: halo inputs read straight-line (one selected base, issued with the main reads, one counted wait) instead of a branch tree with an LDS round trip per value; odd chunk's output-tile stor
# speedup vs baseline: 1.0042x; 1.0042x over previous
.LBB0_364:
	s_cmp_lg_u32 s30, 0
	v_cndmask_b32_e64 v76, 0, 1, s[28:29]
	s_cselect_b64 s[16:17], -1, 0
	v_cmp_ne_u32_e64 s[14:15], 1, v76
	v_cndmask_b32_e64 v77, 0, 1, s[16:17]
	v_add_u32_e32 v76, s79, v88
	v_cmp_ne_u32_e64 s[16:17], 1, v77
	v_add_u32_e32 v77, 0x4650, v88
	v_cndmask_b32_e64 v218, v77, v76, s[28:29]
	ds_read_u16 v76, v218
	ds_read_u16 v77, v218 offset:144
	ds_read_u16 v78, v218 offset:288
	s_and_b64 s[34:35], s[14:15], s[16:17]
.LBB0_382:
	v_add_u32_e32 v151, s81, v88
	ds_read_u16 v79, v119
	ds_read_u16 v80, v151
	ds_read_u16 v81, v151 offset:144
	ds_read_u16 v82, v151 offset:288
	ds_read_u16 v83, v151 offset:432
	ds_read_u16 v84, v151 offset:576
	ds_read_u16 v85, v151 offset:720
	ds_read_u16 v152, v151 offset:864
	s_waitcnt lgkmcnt(8)
	v_lshlrev_b32_e32 v76, 16, v76
	v_lshlrev_b32_e32 v77, 16, v77
	v_lshlrev_b32_e32 v78, 16, v78
	v_cndmask_b32_e64 v76, v76, 0, s[34:35]
	v_cndmask_b32_e64 v77, v77, 0, s[34:35]
	v_cndmask_b32_e64 v78, v78, 0, s[34:35]
	v_fma_f32 v162, v114, v76, v50
	v_fmac_f32_e32 v162, v115, v77
	v_fma_f32 v163, v114, v77, v50
	s_waitcnt lgkmcnt(7)
	v_lshlrev_b32_e32 v79, 16, v79
	v_fmac_f32_e32 v162, v116, v78
	v_fmac_f32_e32 v163, v115, v78
	v_fma_f32 v164, v114, v78, v50
	s_waitcnt lgkmcnt(6)
	v_lshlrev_b32_e32 v80, 16, v80
	v_fmac_f32_e32 v162, v117, v79
	v_cvt_pk_bf16_f32 v76, v162, v51
	v_fmac_f32_e32 v163, v116, v79
	v_fmac_f32_e32 v164, v115, v79
	v_fma_f32 v165, v114, v79, v50
	s_waitcnt lgkmcnt(5)
	v_lshlrev_b32_e32 v81, 16, v81
	ds_write_b16 v119, v76 offset:36864
	v_fmac_f32_e32 v163, v117, v80
	v_cvt_pk_bf16_f32 v76, v163, v51
	v_fmac_f32_e32 v164, v116, v80
	v_fmac_f32_e32 v165, v115, v80
	v_fma_f32 v166, v114, v80, v50
	s_waitcnt lgkmcnt(5)
	v_lshlrev_b32_e32 v82, 16, v82
	ds_write_b16 v151, v76 offset:36864
	v_fmac_f32_e32 v164, v117, v81
	v_cvt_pk_bf16_f32 v76, v164, v51
	v_fmac_f32_e32 v165, v116, v81
	v_fmac_f32_e32 v166, v115, v81
	v_fma_f32 v167, v114, v81, v50
	s_waitcnt lgkmcnt(5)
	v_lshlrev_b32_e32 v83, 16, v83
	ds_write_b16 v151, v76 offset:37008
	v_fmac_f32_e32 v165, v117, v82
	v_cvt_pk_bf16_f32 v76, v165, v51
	v_fmac_f32_e32 v166, v116, v82
	v_fmac_f32_e32 v167, v115, v82
	v_fma_f32 v168, v114, v82, v50
	s_waitcnt lgkmcnt(5)
	v_lshlrev_b32_e32 v84, 16, v84
	ds_write_b16 v151, v76 offset:37152
	v_fmac_f32_e32 v166, v117, v83
	v_cvt_pk_bf16_f32 v76, v166, v51
	v_fmac_f32_e32 v167, v116, v83
	v_fmac_f32_e32 v168, v115, v83
	v_fma_f32 v169, v114, v83, v50
	s_waitcnt lgkmcnt(5)
	v_lshlrev_b32_e32 v85, 16, v85
	ds_write_b16 v151, v76 offset:37296
	v_fmac_f32_e32 v167, v117, v84
	v_cvt_pk_bf16_f32 v76, v167, v51
	v_fmac_f32_e32 v168, v116, v84
	v_fmac_f32_e32 v169, v115, v84
	s_waitcnt lgkmcnt(5)
	v_lshlrev_b32_e32 v152, 16, v152
	ds_write_b16 v151, v76 offset:37440
	v_fmac_f32_e32 v168, v117, v85
	v_cvt_pk_bf16_f32 v76, v168, v51
	v_fmac_f32_e32 v169, v116, v85
	ds_write_b16 v151, v76 offset:37584
	v_fmac_f32_e32 v169, v117, v152
	v_cvt_pk_bf16_f32 v76, v169, v51
	ds_write_b16 v151, v76 offset:37728
	s_waitcnt lgkmcnt(0)
	s_barrier
	ds_read_b128 v[76:79], v150 offset:36864
	ds_read_b128 v[80:83], v150 offset:36928
	s_waitcnt lgkmcnt(1)
	v_mfma_f32_16x16x32_bf16 v[152:155], v[76:79], v[12:15], 0
	s_and_b64 vcc, exec, s[16:17]
	s_waitcnt lgkmcnt(0)
	v_mfma_f32_16x16x32_bf16 v[152:155], v[80:83], v[20:23], v[152:155]
	v_mfma_f32_16x16x32_bf16 v[156:159], v[76:79], v[24:27], 0
	v_mfma_f32_16x16x32_bf16 v[156:159], v[80:83], v[28:31], v[156:159]
	s_nop 5
	v_fma_f32 v84, -v152, s20, v62
	v_fma_f32 v85, -v153, s20, v63
	v_pk_fma_f32 v[154:155], v[154:155], s[20:21], v[62:63] op_sel_hi:[1,0,1] neg_lo:[1,0,0] neg_hi:[1,0,0]
	v_exp_f32_e32 v84, v84
	v_exp_f32_e32 v85, v85
	v_exp_f32_e32 v154, v154
	v_pk_fma_f32 v[152:153], v[156:157], s[20:21], v[64:65] op_sel_hi:[1,0,1] neg_lo:[1,0,0] neg_hi:[1,0,0]
	v_exp_f32_e32 v155, v155
	v_pk_add_f32 v[84:85], v[84:85], 1.0 op_sel_hi:[1,0]
	v_exp_f32_e32 v152, v152
	v_rcp_f32_e32 v84, v84
	v_rcp_f32_e32 v85, v85
	v_exp_f32_e32 v153, v153
	v_pk_mul_f32 v[84:85], v[70:71], v[84:85]
	s_nop 0
	v_exp_f32_e32 v84, v84
	v_exp_f32_e32 v85, v85
	v_pk_add_f32 v[152:153], v[152:153], 1.0 op_sel_hi:[1,0]
	ds_write_b32 v120, v84 offset:64512
	ds_write_b32 v120, v85 offset:64784
	v_pk_fma_f32 v[156:157], v[84:85], v[84:85], 1.0 op_sel_hi:[1,1,0] neg_lo:[1,0,0] neg_hi:[1,0,0]
	v_rcp_f32_e32 v152, v152
	v_rcp_f32_e32 v153, v153
	v_sqrt_f32_e32 v156, v156
	v_sqrt_f32_e32 v157, v157
	v_pk_add_f32 v[84:85], v[154:155], 1.0 op_sel_hi:[1,0]
	v_pk_mul_f32 v[156:157], v[152:153], v[156:157]
	v_pk_fma_f32 v[152:153], v[158:159], s[20:21], v[64:65] op_sel_hi:[1,0,1] neg_lo:[1,0,0] neg_hi:[1,0,0]
	v_rcp_f32_e32 v84, v84
	v_exp_f32_e32 v152, v152
	v_exp_f32_e32 v153, v153
	v_rcp_f32_e32 v85, v85
	ds_write_b32 v121, v156
	ds_write_b32 v122, v157
	v_pk_add_f32 v[152:153], v[152:153], 1.0 op_sel_hi:[1,0]
	v_pk_mul_f32 v[84:85], v[70:71], v[84:85]
	v_rcp_f32_e32 v158, v152
	v_rcp_f32_e32 v159, v153
	v_mfma_f32_16x16x32_bf16 v[152:155], v[76:79], v[32:35], 0
	v_exp_f32_e32 v84, v84
	v_exp_f32_e32 v85, v85
	ds_write_b32 v120, v84 offset:65056
	v_mfma_f32_16x16x32_bf16 v[152:155], v[80:83], v[36:39], v[152:155]
	v_fma_f32 v160, -v84, v84, 1.0
	v_fma_f32 v161, -v85, v85, 1.0
	v_sqrt_f32_e32 v160, v160
	v_mfma_f32_16x16x32_bf16 v[76:79], v[76:79], v[40:43], 0
	v_sqrt_f32_e32 v161, v161
	s_nop 2
	v_pk_fma_f32 v[152:153], v[152:153], s[20:21], v[66:67] op_sel_hi:[1,0,1] neg_lo:[1,0,0] neg_hi:[1,0,0]
	v_pk_mul_f32 v[156:157], v[158:159], v[160:161]
	v_exp_f32_e32 v152, v152
	v_exp_f32_e32 v153, v153
	v_mfma_f32_16x16x32_bf16 v[76:79], v[80:83], v[44:47], v[76:79]
	ds_write_b32 v123, v85 offset:64784
	ds_write_b32 v124, v156
	v_pk_fma_f32 v[84:85], v[154:155], s[20:21], v[66:67] op_sel_hi:[1,0,1] neg_lo:[1,0,0] neg_hi:[1,0,0]
	v_pk_add_f32 v[80:81], v[152:153], 1.0 op_sel_hi:[1,0]
	v_exp_f32_e32 v84, v84
	v_rcp_f32_e32 v80, v80
	v_rcp_f32_e32 v81, v81
	s_nop 0
	v_pk_fma_f32 v[76:77], v[76:77], s[20:21], v[68:69] op_sel_hi:[1,0,1] neg_lo:[1,0,0] neg_hi:[1,0,0]
	v_exp_f32_e32 v85, v85
	v_exp_f32_e32 v76, v76
	v_pk_mul_f32 v[80:81], v[72:73], v[80:81]
	v_exp_f32_e32 v77, v77
	v_exp_f32_e32 v80, v80
	v_exp_f32_e32 v81, v81
	v_pk_fma_f32 v[78:79], v[78:79], s[20:21], v[68:69] op_sel_hi:[1,0,1] neg_lo:[1,0,0] neg_hi:[1,0,0]
	v_pk_add_f32 v[76:77], v[76:77], 1.0 op_sel_hi:[1,0]
	v_exp_f32_e32 v78, v78
	v_pk_fma_f32 v[82:83], v[80:81], v[80:81], 1.0 op_sel_hi:[1,1,0] neg_lo:[1,0,0] neg_hi:[1,0,0]
	v_rcp_f32_e32 v76, v76
	v_rcp_f32_e32 v77, v77
	v_sqrt_f32_e32 v82, v82
	v_sqrt_f32_e32 v83, v83
	v_exp_f32_e32 v79, v79
	ds_write_b32 v125, v157
	ds_write_b32 v120, v80 offset:64576
	v_pk_mul_f32 v[76:77], v[76:77], v[82:83]
	v_pk_add_f32 v[82:83], v[84:85], 1.0 op_sel_hi:[1,0]
	v_pk_add_f32 v[78:79], v[78:79], 1.0 op_sel_hi:[1,0]
	v_rcp_f32_e32 v82, v82
	v_rcp_f32_e32 v83, v83
	v_rcp_f32_e32 v78, v78
	v_rcp_f32_e32 v79, v79
	ds_write_b32 v126, v81 offset:64576
	ds_write_b32 v127, v76
	ds_write_b32 v128, v77
	v_pk_mul_f32 v[82:83], v[72:73], v[82:83]
	s_nop 0
	v_exp_f32_e32 v82, v82
	v_exp_f32_e32 v83, v83
	s_nop 0
	v_pk_fma_f32 v[84:85], v[82:83], v[82:83], 1.0 op_sel_hi:[1,1,0] neg_lo:[1,0,0] neg_hi:[1,0,0]
	s_nop 0
	v_sqrt_f32_e32 v84, v84
	v_sqrt_f32_e32 v85, v85
	s_nop 0
	v_pk_mul_f32 v[76:77], v[78:79], v[84:85]
	ds_write_b32 v129, v82 offset:65056
	ds_write_b32 v130, v83 offset:64576
	ds_write_b32 v131, v76
	ds_write_b32 v132, v77
	s_waitcnt lgkmcnt(0)
	s_barrier
	ds_read_b32 v153, v133 offset:64512
	ds_read_b32 v76, v134
	ds_read_b32 v157, v135 offset:64512
	ds_read_b32 v77, v136
	ds_read_b32 v156, v137 offset:64512
	ds_read_b32 v78, v138
	ds_read_b32 v152, v139 offset:64512
	ds_read_b32 v79, v140
	s_waitcnt lgkmcnt(6)
	v_mul_f32_e32 v82, v162, v76
	v_fma_f32 v76, 0, v153, v82
	s_waitcnt lgkmcnt(4)
	v_mul_f32_e32 v83, v163, v77
	v_fma_f32 v76, v157, v76, v83
	v_mul_f32_e32 v77, v153, v157
	s_waitcnt lgkmcnt(2)
	v_mul_f32_e32 v80, v164, v78
	v_fma_f32 v76, v156, v76, v80
	v_mul_f32_e32 v77, v77, v156
	s_waitcnt lgkmcnt(0)
	v_mul_f32_e32 v81, v165, v79
	ds_read_b32 v155, v141 offset:64512
	ds_read_b32 v78, v142
	ds_read_b32 v154, v143 offset:64512
	ds_read_b32 v79, v144
	ds_read_b32 v85, v145 offset:64512
	ds_read_b32 v158, v146
	ds_read_b32 v84, v147 offset:64512
	ds_read_b32 v159, v148
	v_fma_f32 v76, v152, v76, v81
	v_mul_f32_e32 v77, v77, v152
	s_waitcnt lgkmcnt(6)
	v_mul_f32_e32 v78, v166, v78
	v_fma_f32 v76, v155, v76, v78
	v_mul_f32_e32 v77, v77, v155
	s_waitcnt lgkmcnt(4)
	v_mul_f32_e32 v79, v167, v79
	v_fma_f32 v160, v154, v76, v79
	v_mul_f32_e32 v77, v77, v154
	s_waitcnt lgkmcnt(2)
	v_mul_f32_e32 v76, v168, v158
	v_fma_f32 v158, v85, v160, v76
	v_mul_f32_e32 v160, v77, v85
	s_waitcnt lgkmcnt(0)
	v_mul_f32_e32 v77, v169, v159
	v_mul_f32_e32 v159, v160, v84
	v_fma_f32 v158, v84, v158, v77
	ds_write_b32 v59, v159
	ds_write_b32 v118, v158
	s_waitcnt lgkmcnt(0)
	s_barrier
	s_cbranch_vccnz .LBB0_384
	ds_read_b32 v164, v89
	s_branch .LBB0_385

.LBB0_391:
	s_waitcnt lgkmcnt(0)
	s_barrier
	ds_read_b128 v[212:215], v113
	v_add_co_u32_e32 v216, vcc, 0x7600000, v76
	ds_read_u16 v78, v119 offset:8784
	ds_read_u16 v79, v119 offset:8928
	v_addc_co_u32_e32 v217, vcc, 0, v77, vcc
	ds_read_u16 v80, v119 offset:9072
.LBB0_403:
	ds_read_u16 v81, v119 offset:9216
	ds_read_u16 v82, v151 offset:9216
	ds_read_u16 v83, v151 offset:9360
	ds_read_u16 v84, v151 offset:9504
	ds_read_u16 v85, v151 offset:9648
	ds_read_u16 v154, v151 offset:9792
	ds_read_u16 v155, v151 offset:9936
	ds_read_u16 v156, v151 offset:10080
	s_waitcnt lgkmcnt(8)
	global_store_dwordx4 v[216:217], v[212:215], off offset:2048
	v_lshlrev_b32_e32 v78, 16, v78
	v_lshlrev_b32_e32 v79, 16, v79
	v_lshlrev_b32_e32 v80, 16, v80
	v_fma_f32 v166, v114, v78, v50
	v_fmac_f32_e32 v166, v115, v79
	v_fma_f32 v167, v114, v79, v50
	s_waitcnt lgkmcnt(7)
	v_lshlrev_b32_e32 v81, 16, v81
	v_fmac_f32_e32 v166, v116, v80
	v_fmac_f32_e32 v167, v115, v80
	v_fma_f32 v168, v114, v80, v50
	s_waitcnt lgkmcnt(6)
	v_lshlrev_b32_e32 v82, 16, v82
	v_fmac_f32_e32 v166, v117, v81
	v_cvt_pk_bf16_f32 v78, v166, v51
	v_fmac_f32_e32 v167, v116, v81
	v_fmac_f32_e32 v168, v115, v81
	v_fma_f32 v169, v114, v81, v50
	s_waitcnt lgkmcnt(5)
	v_lshlrev_b32_e32 v83, 16, v83
	ds_write_b16 v119, v78 offset:36864
	v_fmac_f32_e32 v167, v117, v82
	v_cvt_pk_bf16_f32 v78, v167, v51
	v_fmac_f32_e32 v168, v116, v82
	v_fmac_f32_e32 v169, v115, v82
	v_fma_f32 v170, v114, v82, v50
	s_waitcnt lgkmcnt(5)
	v_lshlrev_b32_e32 v84, 16, v84
	ds_write_b16 v151, v78 offset:36864
	v_fmac_f32_e32 v168, v117, v83
	v_cvt_pk_bf16_f32 v78, v168, v51
	v_fmac_f32_e32 v169, v116, v83
	v_fmac_f32_e32 v170, v115, v83
	v_fma_f32 v171, v114, v83, v50
	s_waitcnt lgkmcnt(5)
	v_lshlrev_b32_e32 v85, 16, v85
	ds_write_b16 v151, v78 offset:37008
	v_fmac_f32_e32 v169, v117, v84
	v_cvt_pk_bf16_f32 v78, v169, v51
	v_fmac_f32_e32 v170, v116, v84
	v_fmac_f32_e32 v171, v115, v84
	v_fma_f32 v172, v114, v84, v50
	s_waitcnt lgkmcnt(5)
	v_lshlrev_b32_e32 v154, 16, v154
	ds_write_b16 v151, v78 offset:37152
	v_fmac_f32_e32 v170, v117, v85
	v_cvt_pk_bf16_f32 v78, v170, v51
	v_fmac_f32_e32 v171, v116, v85
	v_fmac_f32_e32 v172, v115, v85
	v_fma_f32 v173, v114, v85, v50
	s_waitcnt lgkmcnt(5)
	v_lshlrev_b32_e32 v155, 16, v155
	ds_write_b16 v151, v78 offset:37296
	v_fmac_f32_e32 v171, v117, v154
	v_cvt_pk_bf16_f32 v78, v171, v51
	v_fmac_f32_e32 v172, v116, v154
	v_fmac_f32_e32 v173, v115, v154
	s_waitcnt lgkmcnt(5)
	v_lshlrev_b32_e32 v156, 16, v156
	ds_write_b16 v151, v78 offset:37440
	v_fmac_f32_e32 v172, v117, v155
	v_cvt_pk_bf16_f32 v78, v172, v51
	v_fmac_f32_e32 v173, v116, v155
	ds_write_b16 v151, v78 offset:37584
	v_fmac_f32_e32 v173, v117, v156
	v_cvt_pk_bf16_f32 v78, v173, v51
	ds_write_b16 v151, v78 offset:37728
	s_waitcnt lgkmcnt(0)
	s_barrier
	ds_read_b128 v[78:81], v150 offset:36864
	ds_read_b128 v[82:85], v150 offset:36928
	s_waitcnt lgkmcnt(1)
	v_mfma_f32_16x16x32_bf16 v[154:157], v[78:81], v[12:15], 0
	s_and_b64 vcc, exec, s[14:15]
	s_waitcnt lgkmcnt(0)
	v_mfma_f32_16x16x32_bf16 v[154:157], v[82:85], v[20:23], v[154:157]
	v_mfma_f32_16x16x32_bf16 v[158:161], v[78:81], v[24:27], 0
	v_mfma_f32_16x16x32_bf16 v[158:161], v[82:85], v[28:31], v[158:161]
	s_nop 5
	v_fma_f32 v154, -v154, s20, v62
	v_fma_f32 v155, -v155, s20, v63
	v_pk_fma_f32 v[156:157], v[156:157], s[20:21], v[62:63] op_sel_hi:[1,0,1] neg_lo:[1,0,0] neg_hi:[1,0,0]
	v_exp_f32_e32 v154, v154
	v_exp_f32_e32 v155, v155
	v_exp_f32_e32 v156, v156
	v_exp_f32_e32 v157, v157
	v_pk_fma_f32 v[158:159], v[158:159], s[20:21], v[64:65] op_sel_hi:[1,0,1] neg_lo:[1,0,0] neg_hi:[1,0,0]
	v_pk_add_f32 v[154:155], v[154:155], 1.0 op_sel_hi:[1,0]
	v_exp_f32_e32 v158, v158
	v_rcp_f32_e32 v154, v154
	v_rcp_f32_e32 v155, v155
	v_exp_f32_e32 v159, v159
	v_pk_mul_f32 v[154:155], v[70:71], v[154:155]
	s_nop 0
	v_exp_f32_e32 v154, v154
	v_exp_f32_e32 v155, v155
	ds_write_b32 v120, v154 offset:64512
	ds_write_b32 v120, v155 offset:64784
	v_pk_fma_f32 v[162:163], v[154:155], v[154:155], 1.0 op_sel_hi:[1,1,0] neg_lo:[1,0,0] neg_hi:[1,0,0]
	v_pk_add_f32 v[154:155], v[156:157], 1.0 op_sel_hi:[1,0]
	v_pk_fma_f32 v[156:157], v[160:161], s[20:21], v[64:65] op_sel_hi:[1,0,1] neg_lo:[1,0,0] neg_hi:[1,0,0]
	v_rcp_f32_e32 v154, v154
	v_rcp_f32_e32 v155, v155
	v_pk_add_f32 v[158:159], v[158:159], 1.0 op_sel_hi:[1,0]
	v_exp_f32_e32 v156, v156
	v_exp_f32_e32 v157, v157
	v_rcp_f32_e32 v158, v158
	v_rcp_f32_e32 v159, v159
	v_sqrt_f32_e32 v162, v162
	v_sqrt_f32_e32 v163, v163
	v_pk_mul_f32 v[154:155], v[70:71], v[154:155]
	v_pk_mul_f32 v[158:159], v[158:159], v[162:163]
	v_exp_f32_e32 v160, v154
	v_exp_f32_e32 v161, v155
	v_pk_add_f32 v[154:155], v[156:157], 1.0 op_sel_hi:[1,0]
	ds_write_b32 v121, v158
	v_rcp_f32_e32 v162, v154
	v_rcp_f32_e32 v163, v155
	v_mfma_f32_16x16x32_bf16 v[154:157], v[78:81], v[32:35], 0
	v_fma_f32 v164, -v160, v160, 1.0
	v_fma_f32 v165, -v161, v161, 1.0
	ds_write_b32 v122, v159
	v_sqrt_f32_e32 v164, v164
	v_mfma_f32_16x16x32_bf16 v[154:157], v[82:85], v[36:39], v[154:157]
	v_sqrt_f32_e32 v165, v165
	ds_write_b32 v120, v160 offset:65056
	v_pk_mul_f32 v[158:159], v[162:163], v[164:165]
	v_mfma_f32_16x16x32_bf16 v[78:81], v[78:81], v[40:43], 0
	s_nop 3
	v_fma_f32 v154, -v154, s20, v66
	v_fma_f32 v155, -v155, s20, v67
	ds_write_b32 v123, v161 offset:64784
	ds_write_b32 v124, v158
	v_exp_f32_e32 v154, v154
	v_exp_f32_e32 v155, v155
	v_mfma_f32_16x16x32_bf16 v[78:81], v[82:85], v[44:47], v[78:81]
	ds_write_b32 v125, v159
	v_pk_add_f32 v[82:83], v[154:155], 1.0 op_sel_hi:[1,0]
	s_nop 0
	v_rcp_f32_e32 v82, v82
	v_rcp_f32_e32 v83, v83
	s_nop 2
	v_pk_fma_f32 v[78:79], v[78:79], s[20:21], v[68:69] op_sel_hi:[1,0,1] neg_lo:[1,0,0] neg_hi:[1,0,0]
	v_pk_fma_f32 v[154:155], v[156:157], s[20:21], v[66:67] op_sel_hi:[1,0,1] neg_lo:[1,0,0] neg_hi:[1,0,0]
	v_exp_f32_e32 v78, v78
	v_pk_mul_f32 v[82:83], v[72:73], v[82:83]
	v_exp_f32_e32 v79, v79
	v_exp_f32_e32 v82, v82
	v_exp_f32_e32 v83, v83
	v_exp_f32_e32 v154, v154
	v_pk_add_f32 v[78:79], v[78:79], 1.0 op_sel_hi:[1,0]
	v_exp_f32_e32 v155, v155
	v_pk_fma_f32 v[84:85], v[82:83], v[82:83], 1.0 op_sel_hi:[1,1,0] neg_lo:[1,0,0] neg_hi:[1,0,0]
	v_rcp_f32_e32 v78, v78
	v_rcp_f32_e32 v79, v79
	v_sqrt_f32_e32 v84, v84
	v_sqrt_f32_e32 v85, v85
	v_pk_fma_f32 v[80:81], v[80:81], s[20:21], v[68:69] op_sel_hi:[1,0,1] neg_lo:[1,0,0] neg_hi:[1,0,0]
	ds_write_b32 v120, v82 offset:64576
	v_exp_f32_e32 v80, v80
	v_pk_mul_f32 v[78:79], v[78:79], v[84:85]
	v_pk_add_f32 v[84:85], v[154:155], 1.0 op_sel_hi:[1,0]
	v_exp_f32_e32 v81, v81
	v_rcp_f32_e32 v84, v84
	v_rcp_f32_e32 v85, v85
	ds_write_b32 v126, v83 offset:64576
	ds_write_b32 v127, v78
	ds_write_b32 v128, v79
	v_pk_add_f32 v[80:81], v[80:81], 1.0 op_sel_hi:[1,0]
	v_pk_mul_f32 v[84:85], v[72:73], v[84:85]
	s_nop 0
	v_exp_f32_e32 v84, v84
	v_exp_f32_e32 v85, v85
	v_rcp_f32_e32 v80, v80
	v_rcp_f32_e32 v81, v81
	v_pk_fma_f32 v[154:155], v[84:85], v[84:85], 1.0 op_sel_hi:[1,1,0] neg_lo:[1,0,0] neg_hi:[1,0,0]
	s_nop 0
	v_sqrt_f32_e32 v154, v154
	v_sqrt_f32_e32 v155, v155
	s_nop 0
	v_pk_mul_f32 v[78:79], v[80:81], v[154:155]
	ds_write_b32 v129, v84 offset:65056
	ds_write_b32 v130, v85 offset:64576
	ds_write_b32 v131, v78
	ds_write_b32 v132, v79
	s_waitcnt lgkmcnt(0)
	s_barrier
	ds_read_b32 v160, v133 offset:64512
	ds_read_b32 v78, v134
	ds_read_b32 v161, v135 offset:64512
	ds_read_b32 v79, v136
	ds_read_b32 v159, v137 offset:64512
	ds_read_b32 v80, v138
	ds_read_b32 v158, v139 offset:64512
	ds_read_b32 v81, v140
	s_waitcnt lgkmcnt(6)
	v_mul_f32_e32 v84, v166, v78
	v_fma_f32 v78, 0, v160, v84
	s_waitcnt lgkmcnt(4)
	v_mul_f32_e32 v85, v167, v79
	v_fma_f32 v78, v161, v78, v85
	v_mul_f32_e32 v79, v160, v161
	s_waitcnt lgkmcnt(2)
	v_mul_f32_e32 v82, v168, v80
	s_waitcnt lgkmcnt(0)
	v_mul_f32_e32 v83, v169, v81
	ds_read_b32 v157, v141 offset:64512
	ds_read_b32 v80, v142
	ds_read_b32 v156, v143 offset:64512
	ds_read_b32 v81, v144
	ds_read_b32 v155, v145 offset:64512
	ds_read_b32 v162, v146
	ds_read_b32 v154, v147 offset:64512
	ds_read_b32 v163, v148
	v_fma_f32 v78, v159, v78, v82
	v_mul_f32_e32 v79, v79, v159
	v_fma_f32 v78, v158, v78, v83
	v_mul_f32_e32 v79, v79, v158
	s_waitcnt lgkmcnt(6)
	v_mul_f32_e32 v80, v170, v80
	v_fma_f32 v78, v157, v78, v80
	v_mul_f32_e32 v79, v79, v157
	s_waitcnt lgkmcnt(4)
	v_mul_f32_e32 v81, v171, v81
	v_fma_f32 v164, v156, v78, v81
	v_mul_f32_e32 v79, v79, v156
	s_waitcnt lgkmcnt(2)
	v_mul_f32_e32 v78, v172, v162
	v_fma_f32 v162, v155, v164, v78
	v_mul_f32_e32 v164, v79, v155
	s_waitcnt lgkmcnt(0)
	v_mul_f32_e32 v79, v173, v163
	v_fma_f32 v162, v154, v162, v79
	v_mul_f32_e32 v163, v164, v154
	ds_write_b32 v59, v163
	ds_write_b32 v118, v162
	s_waitcnt lgkmcnt(0)
	s_barrier
	ds_read_b32 v172, v89 offset:256
	ds_read_b32 v173, v93
	ds_read_b32 v174, v94
	ds_read_b32 v170, v95
	ds_read_b32 v171, v96
	ds_read_b32 v168, v97
	ds_read_b32 v169, v98
	ds_read_b32 v165, v99
	ds_read_b32 v167, v100
	ds_read_b32 v166, v101
	ds_read_b32 v163, v102
	ds_read_b32 v162, v103
	ds_read_b32 v164, v104
	s_cbranch_vccnz .LBB0_405
	ds_read_b32 v175, v105
	ds_read_b32 v176, v106
	s_waitcnt lgkmcnt(0)
	v_fmac_f32_e32 v175, v172, v176
	v_mov_b32_e32 v172, v175
